# baseline (speedup 1.0000x reference)
; __device__ __forceinline__ float gfac(float g1, float g2, bool fin) { const float d1 = __builtin_amdgcn_rcpf(1.0f + __expf(-g1)); return fin ? d1 : d1 * (1.0f + __expf(-g2)); }
;     __device__ __forceinline__ void operator()(f32x4 (&acc)[2][2][4][2], const Unit& u, int wr, int wc, int fr, int fq) const {
;         const int row0 = u.pm * BM + wr * 64 + fr, col0 = u.pn * BM + wc * 32 + 8 * fq;
;         const bool fin = u.s == 2;
;         const char* g1 = ga + (u.s == 0 ? 0L : (u.s == 1 ? G1 : G2));
;         const char* g2 = ga + (u.s == 0 ? G1 : G2);
; #pragma unroll
;         for (int ai = 0; ai < 2; ++ai)
; #pragma unroll
;             for (int mp = 0; mp < 2; ++mp) {
;                 u32x4 x1[2][2], x2[2][2];
; #pragma unroll
;                 for (int mi = 0; mi < 2; ++mi) { const int row = row0 + ai * HALF + (2 * mp + mi) * 16; const unsigned goff = ((unsigned)row * (unsigned)ldg + (unsigned)col0) * 2u;
; #pragma unroll
;                     for (int bj = 0; bj < 2; ++bj) { x1[mi][bj] = *(const u32x4*)(g1 + goff + bj * HALF * 2); x2[mi][bj] = x1[mi][bj]; if (!fin) x2[mi][bj] = *(const u32x4*)(g2 + goff + bj * HALF * 2); } }
; #pragma unroll
;                 for (int mi = 0; mi < 2; ++mi) { const int m = 2 * mp + mi; const int row = row0 + ai * HALF + m * 16; const unsigned moff = ((unsigned)row * 2048u + (unsigned)col0) * 2u;
; #pragma unroll
;                     for (int bj = 0; bj < 2; ++bj) { const u32x4 p = x1[mi][bj], q = x2[mi][bj];
;                         f32x4 a0 = acc[ai][bj][m][0], a1 = acc[ai][bj][m][1];
;                         a0[0] *= gfac(bf_lo(p.x), bf_lo(q.x), fin); a0[1] *= gfac(bf_hi(p.x), bf_hi(q.x), fin); a0[2] *= gfac(bf_lo(p.y), bf_lo(q.y), fin); a0[3] *= gfac(bf_hi(p.y), bf_hi(q.y), fin);
;                         a1[0] *= gfac(bf_lo(p.z), bf_lo(q.z), fin); a1[1] *= gfac(bf_hi(p.z), bf_hi(q.z), fin); a1[2] *= gfac(bf_lo(p.w), bf_lo(q.w), fin); a1[3] *= gfac(bf_hi(p.w), bf_hi(q.w), fin);
;                         acc[ai][bj][m][0] = a0; acc[ai][bj][m][1] = a1;
;                         if (fin) { u32x4 w; w.x = cvt_pk_bf16(a0[0], a0[1]); w.y = cvt_pk_bf16(a0[2], a0[3]); w.z = cvt_pk_bf16(a1[0], a1[1]); w.w = cvt_pk_bf16(a1[2], a1[3]);
;                             *(u32x4*)((char*)MG + moff + bj * HALF * 2) = w; } } }
;                 asm volatile("" ::: "memory"); }
.LBB0_460:
	s_cmp_eq_u32 s20, 2
	s_cselect_b64 s[6:7], -1, 0
	s_cmp_lg_u32 s20, 2
	v_lshl_or_b32 v192, s22, 8, v171
	s_cselect_b64 s[8:9], -1, 0
	s_cmp_eq_u32 s20, 1
	s_movk_i32 s22, 0x1000
	s_cselect_b32 s20, s22, 0x2000
	s_and_b64 s[34:35], s[10:11], exec
	v_lshl_add_u32 v193, s33, 8, v33
	s_cselect_b32 s20, 0, s20
	s_add_u32 s34, s50, s20
	v_mad_u64_u32 v[194:195], s[36:37], v193, s63, v[192:193]
	s_addc_u32 s35, s51, 0
	v_lshlrev_b32_e32 v130, 1, v194
	global_load_dwordx4 v[154:157], v130, s[34:35]
	s_and_b64 s[10:11], s[10:11], exec
	s_cselect_b32 s10, s22, 0x2000
	s_add_u32 s36, s50, s10
	v_mov_b32_e32 v131, v32
	s_addc_u32 s37, s51, 0
	v_lshl_add_u64 v[166:167], s[36:37], 0, v[130:131]
	v_lshl_add_u64 v[164:165], s[34:35], 0, v[130:131]
	global_load_dwordx4 v[150:153], v[164:165], off offset:256
	v_lshl_add_u32 v164, v194, 1, v213
	global_load_dwordx4 v[142:145], v164, s[34:35]
	v_mov_b32_e32 v165, v32
	v_lshl_add_u64 v[196:197], s[36:37], 0, v[164:165]
	v_lshl_add_u64 v[164:165], s[34:35], 0, v[164:165]
	global_load_dwordx4 v[134:137], v[164:165], off offset:256
	s_and_b64 vcc, exec, s[6:7]
	s_cbranch_vccnz .Lef_i0
	global_load_dwordx4 v[158:161], v[166:167], off
	global_load_dwordx4 v[146:149], v[166:167], off offset:256
	global_load_dwordx4 v[138:141], v[196:197], off
	global_load_dwordx4 v[130:133], v[196:197], off offset:256
.Lef_i0:
	s_waitcnt vmcnt(0)
	s_and_b64 vcc, exec, s[6:7]
	s_cbranch_vccz .Lef_w0
	v_mov_b64_e32 v[158:159], v[154:155]
	v_mov_b64_e32 v[160:161], v[156:157]
	v_mov_b64_e32 v[146:147], v[150:151]
	v_mov_b64_e32 v[148:149], v[152:153]
	v_mov_b64_e32 v[138:139], v[142:143]
	v_mov_b64_e32 v[140:141], v[144:145]
	v_mov_b64_e32 v[130:131], v[134:135]
	v_mov_b64_e32 v[132:133], v[136:137]
.Lef_w0:
	s_nop 1
	v_lshl_add_u32 v164, v194, 1, v214
	global_load_dwordx4 v[248:251], v164, s[34:35]
	v_mov_b32_e32 v165, v32
	v_lshl_add_u64 v[166:167], s[36:37], 0, v[164:165]
	v_lshl_add_u64 v[164:165], s[34:35], 0, v[164:165]
	global_load_dwordx4 v[240:243], v[164:165], off offset:256
	v_lshl_add_u32 v164, v194, 1, v215
	global_load_dwordx4 v[232:235], v164, s[34:35]
	v_mov_b32_e32 v165, v32
	v_lshl_add_u64 v[196:197], s[36:37], 0, v[164:165]
	v_lshl_add_u64 v[164:165], s[34:35], 0, v[164:165]
	global_load_dwordx4 v[224:227], v[164:165], off offset:256
	s_and_b64 vcc, exec, s[6:7]
	s_cbranch_vccnz .Lef_i1
	global_load_dwordx4 v[244:247], v[166:167], off
	global_load_dwordx4 v[236:239], v[166:167], off offset:256
	global_load_dwordx4 v[228:231], v[196:197], off
	global_load_dwordx4 v[220:223], v[196:197], off offset:256
.Lef_i1:
.LBB0_468:
	v_lshlrev_b32_e32 v165, 16, v154
	v_mul_f32_e32 v165, 0xbfb8aa3b, v165
	v_exp_f32_e32 v165, v165
	v_lshlrev_b32_e32 v164, 1, v192
	v_lshl_add_u32 v192, v193, 12, v164
	v_lshlrev_b32_e32 v164, 16, v158
	v_and_b32_e32 v154, 0xffff0000, v154
	v_mul_f32_e32 v164, 0xbfb8aa3b, v164
	v_mul_f32_e32 v154, 0xbfb8aa3b, v154
	v_add_f32_e32 v165, 1.0, v165
	v_exp_f32_e32 v164, v164
	v_exp_f32_e32 v154, v154
	v_rcp_f32_e32 v165, v165
	v_and_b32_e32 v158, 0xffff0000, v158
	v_mul_f32_e32 v158, 0xbfb8aa3b, v158
	v_add_f32_e32 v164, 1.0, v164
	v_add_f32_e32 v154, 1.0, v154
	v_exp_f32_e32 v158, v158
	v_mul_f32_e32 v164, v165, v164
	v_rcp_f32_e32 v154, v154
	v_cndmask_b32_e64 v164, v164, v165, s[6:7]
	v_mul_f32_e32 v126, v126, v164
	v_lshlrev_b32_e32 v164, 16, v155
	v_add_f32_e32 v158, 1.0, v158
	v_mul_f32_e32 v164, 0xbfb8aa3b, v164
	v_mul_f32_e32 v158, v154, v158
	v_exp_f32_e32 v164, v164
	v_cndmask_b32_e64 v154, v158, v154, s[6:7]
	v_and_b32_e32 v155, 0xffff0000, v155
	v_mul_f32_e32 v127, v127, v154
	v_lshlrev_b32_e32 v154, 16, v159
	v_mul_f32_e32 v155, 0xbfb8aa3b, v155
	v_mul_f32_e32 v154, 0xbfb8aa3b, v154
	v_exp_f32_e32 v155, v155
	v_add_f32_e32 v158, 1.0, v164
	v_exp_f32_e32 v154, v154
	v_rcp_f32_e32 v158, v158
	v_and_b32_e32 v159, 0xffff0000, v159
	v_mul_f32_e32 v159, 0xbfb8aa3b, v159
	v_add_f32_e32 v155, 1.0, v155
	v_exp_f32_e32 v159, v159
	v_add_f32_e32 v154, 1.0, v154
	v_rcp_f32_e32 v155, v155
	v_mul_f32_e32 v154, v158, v154
	v_cndmask_b32_e64 v154, v154, v158, s[6:7]
	v_lshlrev_b32_e32 v158, 16, v156
	v_mul_f32_e32 v128, v128, v154
	v_add_f32_e32 v154, 1.0, v159
	v_mul_f32_e32 v158, 0xbfb8aa3b, v158
	v_mul_f32_e32 v154, v155, v154
	v_exp_f32_e32 v158, v158
	v_cndmask_b32_e64 v154, v154, v155, s[6:7]
	v_and_b32_e32 v156, 0xffff0000, v156
	v_mul_f32_e32 v129, v129, v154
	v_lshlrev_b32_e32 v154, 16, v160
	v_mul_f32_e32 v156, 0xbfb8aa3b, v156
	v_mul_f32_e32 v154, 0xbfb8aa3b, v154
	v_exp_f32_e32 v156, v156
	v_add_f32_e32 v155, 1.0, v158
	v_exp_f32_e32 v154, v154
	v_rcp_f32_e32 v155, v155
	v_and_b32_e32 v158, 0xffff0000, v160
	v_mul_f32_e32 v158, 0xbfb8aa3b, v158
	v_add_f32_e32 v156, 1.0, v156
	v_exp_f32_e32 v158, v158
	v_add_f32_e32 v154, 1.0, v154
	v_rcp_f32_e32 v156, v156
	v_mul_f32_e32 v154, v155, v154
	v_cndmask_b32_e64 v154, v154, v155, s[6:7]
	v_lshlrev_b32_e32 v155, 16, v157
	v_mul_f32_e32 v122, v122, v154
	v_add_f32_e32 v154, 1.0, v158
	v_mul_f32_e32 v155, 0xbfb8aa3b, v155
	v_mul_f32_e32 v154, v156, v154
	v_exp_f32_e32 v155, v155
	v_cndmask_b32_e64 v154, v154, v156, s[6:7]
	v_and_b32_e32 v156, 0xffff0000, v157
	v_mul_f32_e32 v123, v123, v154
	v_lshlrev_b32_e32 v154, 16, v161
	v_mul_f32_e32 v156, 0xbfb8aa3b, v156
	v_mul_f32_e32 v154, 0xbfb8aa3b, v154
	v_exp_f32_e32 v156, v156
	v_add_f32_e32 v155, 1.0, v155
	v_exp_f32_e32 v154, v154
	v_rcp_f32_e32 v155, v155
	v_and_b32_e32 v157, 0xffff0000, v161
	v_mul_f32_e32 v157, 0xbfb8aa3b, v157
	v_add_f32_e32 v156, 1.0, v156
	v_exp_f32_e32 v157, v157
	v_add_f32_e32 v154, 1.0, v154
	v_rcp_f32_e32 v156, v156
	v_mul_f32_e32 v154, v155, v154
	v_cndmask_b32_e64 v154, v154, v155, s[6:7]
	v_mul_f32_e32 v124, v124, v154
	v_add_f32_e32 v154, 1.0, v157
	v_mul_f32_e32 v154, v156, v154
	v_cndmask_b32_e64 v154, v154, v156, s[6:7]
	v_mov_b32_e32 v193, v32
	v_mul_f32_e32 v125, v125, v154
	v_cndmask_b32_e64 v154, 0, 1, s[6:7]
	v_cmp_ne_u32_e64 s[8:9], 1, v154
	s_andn2_b64 vcc, exec, s[6:7]
	v_lshl_add_u64 v[154:155], s[16:17], 0, v[192:193]
	s_cbranch_vccnz .LBB0_470
	v_cvt_pk_bf16_f32 v156, v126, v127
	v_cvt_pk_bf16_f32 v157, v128, v129
	v_cvt_pk_bf16_f32 v158, v122, v123
	v_cvt_pk_bf16_f32 v159, v124, v125
	global_store_dwordx4 v[154:155], v[156:159], off

; __device__ __forceinline__ unsigned cvt_pk_bf16(float lo, float hi) { unsigned r; asm volatile("v_cvt_pk_bf16_f32 %0, %1, %2" : "=v"(r) : "v"(lo), "v"(hi)); return r; }
; __device__ __forceinline__ float bf_lo(unsigned w) { return __uint_as_float(w << 16); }
; __device__ __forceinline__ float bf_hi(unsigned w) { return __uint_as_float(w & 0xffff0000u); }
; __device__ __forceinline__ float gfac(float g1, float g2, bool fin) { const float d1 = __builtin_amdgcn_rcpf(1.0f + __expf(-g1)); return fin ? d1 : d1 * (1.0f + __expf(-g2)); }
;     __device__ __forceinline__ void operator()(f32x4 (&acc)[2][2][4][2], const Unit& u, int wr, int wc, int fr, int fq) const {
;     ...
;                 for (int mi = 0; mi < 2; ++mi) { const int row = row0 + ai * HALF + (2 * mp + mi) * 16; const unsigned goff = ((unsigned)row * (unsigned)ldg + (unsigned)col0) * 2u;
; #pragma unroll
;                     for (int bj = 0; bj < 2; ++bj) { x1[mi][bj] = *(const u32x4*)(g1 + goff + bj * HALF * 2); x2[mi][bj] = x1[mi][bj]; if (!fin) x2[mi][bj] = *(const u32x4*)(g2 + goff + bj * HALF * 2); } }
; #pragma unroll
;                 for (int mi = 0; mi < 2; ++mi) { const int m = 2 * mp + mi; const int row = row0 + ai * HALF + m * 16; const unsigned moff = ((unsigned)row * 2048u + (unsigned)col0) * 2u;
; #pragma unroll
;                     for (int bj = 0; bj < 2; ++bj) { const u32x4 p = x1[mi][bj], q = x2[mi][bj];
;                         f32x4 a0 = acc[ai][bj][m][0], a1 = acc[ai][bj][m][1];
;                         a0[0] *= gfac(bf_lo(p.x), bf_lo(q.x), fin); a0[1] *= gfac(bf_hi(p.x), bf_hi(q.x), fin); a0[2] *= gfac(bf_lo(p.y), bf_lo(q.y), fin); a0[3] *= gfac(bf_hi(p.y), bf_hi(q.y), fin);
;                         a1[0] *= gfac(bf_lo(p.z), bf_lo(q.z), fin); a1[1] *= gfac(bf_hi(p.z), bf_hi(q.z), fin); a1[2] *= gfac(bf_lo(p.w), bf_lo(q.w), fin); a1[3] *= gfac(bf_hi(p.w), bf_hi(q.w), fin);
;                         acc[ai][bj][m][0] = a0; acc[ai][bj][m][1] = a1;
;                         if (fin) { u32x4 w; w.x = cvt_pk_bf16(a0[0], a0[1]); w.y = cvt_pk_bf16(a0[2], a0[3]); w.z = cvt_pk_bf16(a1[0], a1[1]); w.w = cvt_pk_bf16(a1[2], a1[3]);
;                             *(u32x4*)((char*)MG + moff + bj * HALF * 2) = w; } } }
.LBB0_476:
	s_waitcnt vmcnt(0)
	s_and_b64 vcc, exec, s[6:7]
	s_cbranch_vccz .Lef_w1
	v_mov_b64_e32 v[244:245], v[248:249]
	v_mov_b64_e32 v[246:247], v[250:251]
	v_mov_b64_e32 v[236:237], v[240:241]
	v_mov_b64_e32 v[238:239], v[242:243]
	v_mov_b64_e32 v[228:229], v[232:233]
	v_mov_b64_e32 v[230:231], v[234:235]
	v_mov_b64_e32 v[220:221], v[224:225]
	v_mov_b64_e32 v[222:223], v[226:227]
.Lef_w1:
	s_nop 1
	v_lshl_add_u32 v164, v194, 1, v216
	global_load_dwordx4 v[158:161], v164, s[34:35]
	v_mov_b32_e32 v165, v32
	v_lshl_add_u64 v[166:167], s[36:37], 0, v[164:165]
	v_lshl_add_u64 v[164:165], s[34:35], 0, v[164:165]
	global_load_dwordx4 v[150:153], v[164:165], off offset:256
	v_lshl_add_u32 v164, v194, 1, v217
	global_load_dwordx4 v[142:145], v164, s[34:35]
	v_mov_b32_e32 v165, v32
	v_lshl_add_u64 v[196:197], s[36:37], 0, v[164:165]
	v_lshl_add_u64 v[164:165], s[34:35], 0, v[164:165]
	global_load_dwordx4 v[134:137], v[164:165], off offset:256
	s_and_b64 vcc, exec, s[6:7]
	s_cbranch_vccnz .Lef_i2
	global_load_dwordx4 v[154:157], v[166:167], off
	global_load_dwordx4 v[146:149], v[166:167], off offset:256
	global_load_dwordx4 v[138:141], v[196:197], off
	global_load_dwordx4 v[130:133], v[196:197], off offset:256
.Lef_i2:
.LBB0_484:
	v_lshlrev_b32_e32 v164, 16, v248
	v_mul_f32_e32 v164, 0xbfb8aa3b, v164
	v_exp_f32_e32 v166, v164
	v_lshlrev_b32_e32 v167, 16, v244
	v_and_b32_e32 v248, 0xffff0000, v248
	v_mul_f32_e32 v167, 0xbfb8aa3b, v167
	v_mul_f32_e32 v248, 0xbfb8aa3b, v248
	v_add_f32_e32 v166, 1.0, v166
	v_exp_f32_e32 v167, v167
	v_exp_f32_e32 v248, v248
	v_rcp_f32_e32 v166, v166
	v_and_b32_e32 v244, 0xffff0000, v244
	v_mul_f32_e32 v244, 0xbfb8aa3b, v244
	v_add_f32_e32 v167, 1.0, v167
	v_add_f32_e32 v248, 1.0, v248
	v_exp_f32_e32 v244, v244
	v_mul_f32_e32 v167, v166, v167
	v_rcp_f32_e32 v248, v248
	v_cndmask_b32_e64 v166, v167, v166, s[6:7]
	v_mul_f32_e32 v110, v110, v166
	v_lshlrev_b32_e32 v166, 16, v249
	v_add_f32_e32 v244, 1.0, v244
	v_mul_f32_e32 v166, 0xbfb8aa3b, v166
	v_mul_f32_e32 v244, v248, v244
	v_exp_f32_e32 v166, v166
	v_cndmask_b32_e64 v244, v244, v248, s[6:7]
	v_mul_f32_e32 v111, v111, v244
	v_lshlrev_b32_e32 v244, 16, v245
	v_and_b32_e32 v249, 0xffff0000, v249
	v_mul_f32_e32 v244, 0xbfb8aa3b, v244
	v_mul_f32_e32 v249, 0xbfb8aa3b, v249
	v_add_f32_e32 v248, 1.0, v166
	v_exp_f32_e32 v244, v244
	v_exp_f32_e32 v249, v249
	v_rcp_f32_e32 v248, v248
	v_and_b32_e32 v245, 0xffff0000, v245
	v_mul_f32_e32 v245, 0xbfb8aa3b, v245
	v_exp_f32_e32 v245, v245
	v_add_f32_e32 v244, 1.0, v244
	v_add_f32_e32 v249, 1.0, v249
	v_mul_f32_e32 v244, v248, v244
	v_rcp_f32_e32 v249, v249
	v_cndmask_b32_e64 v244, v244, v248, s[6:7]
	v_mul_f32_e32 v112, v112, v244
	v_add_f32_e32 v244, 1.0, v245
	v_lshlrev_b32_e32 v245, 16, v250
	v_mul_f32_e32 v245, 0xbfb8aa3b, v245
	v_mul_f32_e32 v244, v249, v244
	v_exp_f32_e32 v245, v245
	v_cndmask_b32_e64 v244, v244, v249, s[6:7]
	v_and_b32_e32 v248, 0xffff0000, v250
	v_mul_f32_e32 v113, v113, v244
	v_lshlrev_b32_e32 v244, 16, v246
	v_mul_f32_e32 v248, 0xbfb8aa3b, v248
	v_mul_f32_e32 v244, 0xbfb8aa3b, v244
	v_exp_f32_e32 v248, v248
	v_add_f32_e32 v245, 1.0, v245
	v_exp_f32_e32 v244, v244
	v_rcp_f32_e32 v245, v245
	v_and_b32_e32 v246, 0xffff0000, v246
	v_mul_f32_e32 v246, 0xbfb8aa3b, v246
	v_add_f32_e32 v248, 1.0, v248
	v_exp_f32_e32 v246, v246
	v_add_f32_e32 v244, 1.0, v244
	v_rcp_f32_e32 v248, v248
	v_mul_f32_e32 v244, v245, v244
	v_cndmask_b32_e64 v244, v244, v245, s[6:7]
	v_lshlrev_b32_e32 v245, 16, v251
	v_mul_f32_e32 v106, v106, v244
	v_add_f32_e32 v244, 1.0, v246
	v_mul_f32_e32 v245, 0xbfb8aa3b, v245
	v_mul_f32_e32 v244, v248, v244
	v_exp_f32_e32 v245, v245
	v_cndmask_b32_e64 v244, v244, v248, s[6:7]
	v_and_b32_e32 v246, 0xffff0000, v251
	v_mul_f32_e32 v107, v107, v244
	v_lshlrev_b32_e32 v244, 16, v247
	v_mul_f32_e32 v246, 0xbfb8aa3b, v246
	v_mul_f32_e32 v244, 0xbfb8aa3b, v244
	v_exp_f32_e32 v246, v246
	v_add_f32_e32 v245, 1.0, v245
	v_exp_f32_e32 v244, v244
	v_rcp_f32_e32 v245, v245
	v_and_b32_e32 v247, 0xffff0000, v247
	v_mul_f32_e32 v247, 0xbfb8aa3b, v247
	v_add_f32_e32 v246, 1.0, v246
	v_exp_f32_e32 v247, v247
	v_add_f32_e32 v244, 1.0, v244
	v_rcp_f32_e32 v246, v246
	v_mul_f32_e32 v244, v245, v244
	v_cndmask_b32_e64 v244, v244, v245, s[6:7]
	v_mul_f32_e32 v108, v108, v244
	v_add_f32_e32 v244, 1.0, v247
	v_mul_f32_e32 v244, v246, v244
	v_add_u32_e32 v164, 0x20000, v192
	v_mov_b32_e32 v165, v32
	v_cndmask_b32_e64 v244, v244, v246, s[6:7]
	v_mul_f32_e32 v109, v109, v244
	s_and_b64 vcc, exec, s[8:9]
	v_lshl_add_u64 v[244:245], s[16:17], 0, v[164:165]
	s_cbranch_vccnz .LBB0_486
	v_cvt_pk_bf16_f32 v246, v110, v111
	v_cvt_pk_bf16_f32 v247, v112, v113
	v_cvt_pk_bf16_f32 v248, v106, v107
	v_cvt_pk_bf16_f32 v249, v108, v109
	global_store_dwordx4 v[244:245], v[246:249], off
; __device__ __forceinline__ unsigned cvt_pk_bf16(float lo, float hi) { unsigned r; asm volatile("v_cvt_pk_bf16_f32 %0, %1, %2" : "=v"(r) : "v"(lo), "v"(hi)); return r; }
; __device__ __forceinline__ float bf_lo(unsigned w) { return __uint_as_float(w << 16); }
; __device__ __forceinline__ float bf_hi(unsigned w) { return __uint_as_float(w & 0xffff0000u); }
; __device__ __forceinline__ float gfac(float g1, float g2, bool fin) { const float d1 = __builtin_amdgcn_rcpf(1.0f + __expf(-g1)); return fin ? d1 : d1 * (1.0f + __expf(-g2)); }
;     __device__ __forceinline__ void operator()(f32x4 (&acc)[2][2][4][2], const Unit& u, int wr, int wc, int fr, int fq) const {
;     ...
; #pragma unroll
;                 for (int mi = 0; mi < 2; ++mi) { const int m = 2 * mp + mi; const int row = row0 + ai * HALF + m * 16; const unsigned moff = ((unsigned)row * 2048u + (unsigned)col0) * 2u;
; #pragma unroll
;                     for (int bj = 0; bj < 2; ++bj) { const u32x4 p = x1[mi][bj], q = x2[mi][bj];
;                         f32x4 a0 = acc[ai][bj][m][0], a1 = acc[ai][bj][m][1];
;                         a0[0] *= gfac(bf_lo(p.x), bf_lo(q.x), fin); a0[1] *= gfac(bf_hi(p.x), bf_hi(q.x), fin); a0[2] *= gfac(bf_lo(p.y), bf_lo(q.y), fin); a0[3] *= gfac(bf_hi(p.y), bf_hi(q.y), fin);
;                         a1[0] *= gfac(bf_lo(p.z), bf_lo(q.z), fin); a1[1] *= gfac(bf_hi(p.z), bf_hi(q.z), fin); a1[2] *= gfac(bf_lo(p.w), bf_lo(q.w), fin); a1[3] *= gfac(bf_hi(p.w), bf_hi(q.w), fin);
;                         acc[ai][bj][m][0] = a0; acc[ai][bj][m][1] = a1;
;                         if (fin) { u32x4 w; w.x = cvt_pk_bf16(a0[0], a0[1]); w.y = cvt_pk_bf16(a0[2], a0[3]); w.z = cvt_pk_bf16(a1[0], a1[1]); w.w = cvt_pk_bf16(a1[2], a1[3]);
;                             *(u32x4*)((char*)MG + moff + bj * HALF * 2) = w; } } }
.LBB0_486:
	s_nop 1
	v_lshlrev_b32_e32 v246, 16, v240
	v_mul_f32_e32 v246, 0xbfb8aa3b, v246
	v_exp_f32_e32 v246, v246
	v_lshlrev_b32_e32 v247, 16, v236
	v_and_b32_e32 v240, 0xffff0000, v240
	v_mul_f32_e32 v247, 0xbfb8aa3b, v247
	v_mul_f32_e32 v240, 0xbfb8aa3b, v240
	v_exp_f32_e32 v247, v247
	v_add_f32_e32 v246, 1.0, v246
	v_exp_f32_e32 v240, v240
	v_rcp_f32_e32 v246, v246
	v_and_b32_e32 v236, 0xffff0000, v236
	v_mul_f32_e32 v236, 0xbfb8aa3b, v236
	v_add_f32_e32 v247, 1.0, v247
	v_add_f32_e32 v240, 1.0, v240
	v_exp_f32_e32 v236, v236
	v_mul_f32_e32 v247, v246, v247
	v_rcp_f32_e32 v240, v240
	v_cndmask_b32_e64 v246, v247, v246, s[6:7]
	v_mul_f32_e32 v78, v78, v246
	v_lshlrev_b32_e32 v246, 16, v241
	v_add_f32_e32 v236, 1.0, v236
	v_mul_f32_e32 v246, 0xbfb8aa3b, v246
	v_mul_f32_e32 v236, v240, v236
	v_exp_f32_e32 v246, v246
	v_cndmask_b32_e64 v236, v236, v240, s[6:7]
	v_mul_f32_e32 v79, v79, v236
	v_lshlrev_b32_e32 v236, 16, v237
	v_and_b32_e32 v241, 0xffff0000, v241
	v_mul_f32_e32 v236, 0xbfb8aa3b, v236
	v_mul_f32_e32 v241, 0xbfb8aa3b, v241
	v_add_f32_e32 v240, 1.0, v246
	v_exp_f32_e32 v236, v236
	v_exp_f32_e32 v241, v241
	v_rcp_f32_e32 v240, v240
	v_and_b32_e32 v237, 0xffff0000, v237
	v_mul_f32_e32 v237, 0xbfb8aa3b, v237
	v_exp_f32_e32 v237, v237
	v_add_f32_e32 v236, 1.0, v236
	v_add_f32_e32 v241, 1.0, v241
	v_mul_f32_e32 v236, v240, v236
	v_rcp_f32_e32 v241, v241
	v_cndmask_b32_e64 v236, v236, v240, s[6:7]
	v_mul_f32_e32 v80, v80, v236
	v_add_f32_e32 v236, 1.0, v237
	v_lshlrev_b32_e32 v237, 16, v242
	v_mul_f32_e32 v237, 0xbfb8aa3b, v237
	v_mul_f32_e32 v236, v241, v236
	v_exp_f32_e32 v237, v237
	v_cndmask_b32_e64 v236, v236, v241, s[6:7]
	v_and_b32_e32 v240, 0xffff0000, v242
	v_mul_f32_e32 v81, v81, v236
	v_lshlrev_b32_e32 v236, 16, v238
	v_mul_f32_e32 v240, 0xbfb8aa3b, v240
	v_mul_f32_e32 v236, 0xbfb8aa3b, v236
	v_exp_f32_e32 v240, v240
	v_add_f32_e32 v237, 1.0, v237
	v_exp_f32_e32 v236, v236
	v_rcp_f32_e32 v237, v237
	v_and_b32_e32 v238, 0xffff0000, v238
	v_mul_f32_e32 v238, 0xbfb8aa3b, v238
	v_add_f32_e32 v240, 1.0, v240
	v_exp_f32_e32 v238, v238
	v_add_f32_e32 v236, 1.0, v236
	v_rcp_f32_e32 v240, v240
	v_mul_f32_e32 v236, v237, v236
	v_cndmask_b32_e64 v236, v236, v237, s[6:7]
	v_lshlrev_b32_e32 v237, 16, v243
	v_mul_f32_e32 v74, v74, v236
	v_add_f32_e32 v236, 1.0, v238
	v_mul_f32_e32 v237, 0xbfb8aa3b, v237
	v_mul_f32_e32 v236, v240, v236
	v_exp_f32_e32 v237, v237
	v_cndmask_b32_e64 v236, v236, v240, s[6:7]
	v_and_b32_e32 v238, 0xffff0000, v243
	v_mul_f32_e32 v75, v75, v236
	v_lshlrev_b32_e32 v236, 16, v239
	v_mul_f32_e32 v238, 0xbfb8aa3b, v238
	v_mul_f32_e32 v236, 0xbfb8aa3b, v236
	v_exp_f32_e32 v238, v238
	v_add_f32_e32 v237, 1.0, v237
	v_exp_f32_e32 v236, v236
	v_rcp_f32_e32 v237, v237
	v_and_b32_e32 v239, 0xffff0000, v239
	v_mul_f32_e32 v239, 0xbfb8aa3b, v239
	v_add_f32_e32 v238, 1.0, v238
	v_exp_f32_e32 v239, v239
	v_add_f32_e32 v236, 1.0, v236
	v_rcp_f32_e32 v238, v238
	v_mul_f32_e32 v236, v237, v236
	v_cndmask_b32_e64 v236, v236, v237, s[6:7]
	v_mul_f32_e32 v76, v76, v236
	v_add_f32_e32 v236, 1.0, v239
	v_mul_f32_e32 v236, v238, v236
	v_cndmask_b32_e64 v236, v236, v238, s[6:7]
	s_and_b64 vcc, exec, s[8:9]
	v_mul_f32_e32 v77, v77, v236
	s_cbranch_vccnz .LBB0_488
	v_cvt_pk_bf16_f32 v236, v78, v79
	v_cvt_pk_bf16_f32 v237, v80, v81
	v_cvt_pk_bf16_f32 v238, v74, v75
	v_cvt_pk_bf16_f32 v239, v76, v77
	global_store_dwordx4 v[244:245], v[236:239], off offset:256
.LBB0_488:
	s_nop 1
	v_lshlrev_b32_e32 v236, 16, v232
	v_mul_f32_e32 v236, 0xbfb8aa3b, v236
	v_exp_f32_e32 v238, v236
	v_lshlrev_b32_e32 v239, 16, v228
	v_and_b32_e32 v232, 0xffff0000, v232
	v_mul_f32_e32 v239, 0xbfb8aa3b, v239
	v_mul_f32_e32 v232, 0xbfb8aa3b, v232
	v_add_f32_e32 v238, 1.0, v238
	v_exp_f32_e32 v239, v239
	v_exp_f32_e32 v232, v232
	v_rcp_f32_e32 v238, v238
	v_and_b32_e32 v228, 0xffff0000, v228
	v_mul_f32_e32 v228, 0xbfb8aa3b, v228
	v_add_f32_e32 v239, 1.0, v239
	v_add_f32_e32 v232, 1.0, v232
	v_exp_f32_e32 v228, v228
	v_mul_f32_e32 v239, v238, v239
	v_rcp_f32_e32 v232, v232
	v_cndmask_b32_e64 v238, v239, v238, s[6:7]
	v_mul_f32_e32 v102, v102, v238
	v_lshlrev_b32_e32 v238, 16, v233
	v_add_f32_e32 v228, 1.0, v228
	v_mul_f32_e32 v238, 0xbfb8aa3b, v238
	v_mul_f32_e32 v228, v232, v228
	v_exp_f32_e32 v238, v238
	v_cndmask_b32_e64 v228, v228, v232, s[6:7]
	v_mul_f32_e32 v103, v103, v228
	v_lshlrev_b32_e32 v228, 16, v229
	v_and_b32_e32 v233, 0xffff0000, v233
	v_mul_f32_e32 v228, 0xbfb8aa3b, v228
	v_mul_f32_e32 v233, 0xbfb8aa3b, v233
	v_add_f32_e32 v232, 1.0, v238
	v_exp_f32_e32 v228, v228
	v_exp_f32_e32 v233, v233
	v_rcp_f32_e32 v232, v232
	v_and_b32_e32 v229, 0xffff0000, v229
	v_mul_f32_e32 v229, 0xbfb8aa3b, v229
	v_exp_f32_e32 v229, v229
	v_add_f32_e32 v228, 1.0, v228
	v_add_f32_e32 v233, 1.0, v233
	v_mul_f32_e32 v228, v232, v228
	v_rcp_f32_e32 v233, v233
	v_cndmask_b32_e64 v228, v228, v232, s[6:7]
	v_mul_f32_e32 v104, v104, v228
	v_add_f32_e32 v228, 1.0, v229
	v_lshlrev_b32_e32 v229, 16, v234
	v_mul_f32_e32 v229, 0xbfb8aa3b, v229
	v_mul_f32_e32 v228, v233, v228
	v_exp_f32_e32 v229, v229
	v_cndmask_b32_e64 v228, v228, v233, s[6:7]
	v_and_b32_e32 v232, 0xffff0000, v234
	v_mul_f32_e32 v105, v105, v228
	v_lshlrev_b32_e32 v228, 16, v230
	v_mul_f32_e32 v232, 0xbfb8aa3b, v232
	v_mul_f32_e32 v228, 0xbfb8aa3b, v228
	v_exp_f32_e32 v232, v232
	v_add_f32_e32 v229, 1.0, v229
	v_exp_f32_e32 v228, v228
	v_rcp_f32_e32 v229, v229
	v_and_b32_e32 v230, 0xffff0000, v230
	v_mul_f32_e32 v230, 0xbfb8aa3b, v230
	v_add_f32_e32 v232, 1.0, v232
	v_exp_f32_e32 v230, v230
	v_add_f32_e32 v228, 1.0, v228
	v_rcp_f32_e32 v232, v232
	v_mul_f32_e32 v228, v229, v228
	v_cndmask_b32_e64 v228, v228, v229, s[6:7]
	v_lshlrev_b32_e32 v229, 16, v235
	v_mul_f32_e32 v98, v98, v228
	v_add_f32_e32 v228, 1.0, v230
	v_mul_f32_e32 v229, 0xbfb8aa3b, v229
	v_mul_f32_e32 v228, v232, v228
	v_exp_f32_e32 v229, v229
	v_cndmask_b32_e64 v228, v228, v232, s[6:7]
	v_and_b32_e32 v230, 0xffff0000, v235
	v_mul_f32_e32 v99, v99, v228
	v_lshlrev_b32_e32 v228, 16, v231
	v_mul_f32_e32 v230, 0xbfb8aa3b, v230
	v_mul_f32_e32 v228, 0xbfb8aa3b, v228
	v_exp_f32_e32 v230, v230
	v_add_f32_e32 v229, 1.0, v229
	v_exp_f32_e32 v228, v228
	v_rcp_f32_e32 v229, v229
	v_and_b32_e32 v231, 0xffff0000, v231
	v_mul_f32_e32 v231, 0xbfb8aa3b, v231
	v_add_f32_e32 v230, 1.0, v230
	v_exp_f32_e32 v231, v231
	v_add_f32_e32 v228, 1.0, v228
	v_rcp_f32_e32 v230, v230
	v_mul_f32_e32 v228, v229, v228
	v_cndmask_b32_e64 v228, v228, v229, s[6:7]
	v_mul_f32_e32 v100, v100, v228
	v_add_f32_e32 v228, 1.0, v231
	v_mul_f32_e32 v228, v230, v228
	v_add_u32_e32 v236, 0x30000, v192
	v_mov_b32_e32 v237, v32
	v_cndmask_b32_e64 v228, v228, v230, s[6:7]
	v_mul_f32_e32 v101, v101, v228
	s_and_b64 vcc, exec, s[8:9]
	v_lshl_add_u64 v[228:229], s[16:17], 0, v[236:237]
	s_cbranch_vccnz .LBB0_490
	v_cvt_pk_bf16_f32 v230, v102, v103
	v_cvt_pk_bf16_f32 v231, v104, v105
	v_cvt_pk_bf16_f32 v232, v98, v99
	v_cvt_pk_bf16_f32 v233, v100, v101
	global_store_dwordx4 v[228:229], v[230:233], off
; __device__ __forceinline__ unsigned cvt_pk_bf16(float lo, float hi) { unsigned r; asm volatile("v_cvt_pk_bf16_f32 %0, %1, %2" : "=v"(r) : "v"(lo), "v"(hi)); return r; }
; __device__ __forceinline__ float bf_lo(unsigned w) { return __uint_as_float(w << 16); }
; __device__ __forceinline__ float bf_hi(unsigned w) { return __uint_as_float(w & 0xffff0000u); }
; __device__ __forceinline__ float gfac(float g1, float g2, bool fin) { const float d1 = __builtin_amdgcn_rcpf(1.0f + __expf(-g1)); return fin ? d1 : d1 * (1.0f + __expf(-g2)); }
;     __device__ __forceinline__ void operator()(f32x4 (&acc)[2][2][4][2], const Unit& u, int wr, int wc, int fr, int fq) const {
;     ...
; #pragma unroll
;                 for (int mi = 0; mi < 2; ++mi) { const int m = 2 * mp + mi; const int row = row0 + ai * HALF + m * 16; const unsigned moff = ((unsigned)row * 2048u + (unsigned)col0) * 2u;
; #pragma unroll
;                     for (int bj = 0; bj < 2; ++bj) { const u32x4 p = x1[mi][bj], q = x2[mi][bj];
;                         f32x4 a0 = acc[ai][bj][m][0], a1 = acc[ai][bj][m][1];
;                         a0[0] *= gfac(bf_lo(p.x), bf_lo(q.x), fin); a0[1] *= gfac(bf_hi(p.x), bf_hi(q.x), fin); a0[2] *= gfac(bf_lo(p.y), bf_lo(q.y), fin); a0[3] *= gfac(bf_hi(p.y), bf_hi(q.y), fin);
;                         a1[0] *= gfac(bf_lo(p.z), bf_lo(q.z), fin); a1[1] *= gfac(bf_hi(p.z), bf_hi(q.z), fin); a1[2] *= gfac(bf_lo(p.w), bf_lo(q.w), fin); a1[3] *= gfac(bf_hi(p.w), bf_hi(q.w), fin);
;                         acc[ai][bj][m][0] = a0; acc[ai][bj][m][1] = a1;
;                         if (fin) { u32x4 w; w.x = cvt_pk_bf16(a0[0], a0[1]); w.y = cvt_pk_bf16(a0[2], a0[3]); w.z = cvt_pk_bf16(a1[0], a1[1]); w.w = cvt_pk_bf16(a1[2], a1[3]);
;                             *(u32x4*)((char*)MG + moff + bj * HALF * 2) = w; } } }
.LBB0_490:
	s_nop 1
	v_lshlrev_b32_e32 v230, 16, v224
	v_mul_f32_e32 v230, 0xbfb8aa3b, v230
	v_exp_f32_e32 v230, v230
	s_waitcnt vmcnt(0)
	v_lshlrev_b32_e32 v231, 16, v220
	v_and_b32_e32 v224, 0xffff0000, v224
	v_mul_f32_e32 v231, 0xbfb8aa3b, v231
	v_mul_f32_e32 v224, 0xbfb8aa3b, v224
	v_exp_f32_e32 v231, v231
	v_add_f32_e32 v230, 1.0, v230
	v_exp_f32_e32 v224, v224
	v_rcp_f32_e32 v230, v230
	v_and_b32_e32 v220, 0xffff0000, v220
	v_mul_f32_e32 v220, 0xbfb8aa3b, v220
	v_add_f32_e32 v231, 1.0, v231
	v_add_f32_e32 v224, 1.0, v224
	v_exp_f32_e32 v220, v220
	v_mul_f32_e32 v231, v230, v231
	v_rcp_f32_e32 v224, v224
	v_cndmask_b32_e64 v230, v231, v230, s[6:7]
	v_mul_f32_e32 v70, v70, v230
	v_lshlrev_b32_e32 v230, 16, v225
	v_add_f32_e32 v220, 1.0, v220
	v_mul_f32_e32 v230, 0xbfb8aa3b, v230
	v_mul_f32_e32 v220, v224, v220
	v_exp_f32_e32 v230, v230
	v_cndmask_b32_e64 v220, v220, v224, s[6:7]
	v_mul_f32_e32 v71, v71, v220
	v_lshlrev_b32_e32 v220, 16, v221
	v_and_b32_e32 v225, 0xffff0000, v225
	v_mul_f32_e32 v220, 0xbfb8aa3b, v220
	v_mul_f32_e32 v225, 0xbfb8aa3b, v225
	v_add_f32_e32 v224, 1.0, v230
	v_exp_f32_e32 v220, v220
	v_exp_f32_e32 v225, v225
	v_rcp_f32_e32 v224, v224
	v_and_b32_e32 v221, 0xffff0000, v221
	v_mul_f32_e32 v221, 0xbfb8aa3b, v221
	v_exp_f32_e32 v221, v221
	v_add_f32_e32 v220, 1.0, v220
	v_add_f32_e32 v225, 1.0, v225
	v_mul_f32_e32 v220, v224, v220
	v_rcp_f32_e32 v225, v225
	v_cndmask_b32_e64 v220, v220, v224, s[6:7]
	v_mul_f32_e32 v72, v72, v220
	v_add_f32_e32 v220, 1.0, v221
	v_lshlrev_b32_e32 v221, 16, v226
	v_mul_f32_e32 v221, 0xbfb8aa3b, v221
	v_mul_f32_e32 v220, v225, v220
	v_exp_f32_e32 v221, v221
	v_cndmask_b32_e64 v220, v220, v225, s[6:7]
	v_and_b32_e32 v224, 0xffff0000, v226
	v_mul_f32_e32 v73, v73, v220
	v_lshlrev_b32_e32 v220, 16, v222
	v_mul_f32_e32 v224, 0xbfb8aa3b, v224
	v_mul_f32_e32 v220, 0xbfb8aa3b, v220
	v_exp_f32_e32 v224, v224
	v_add_f32_e32 v221, 1.0, v221
	v_exp_f32_e32 v220, v220
	v_rcp_f32_e32 v221, v221
	v_and_b32_e32 v222, 0xffff0000, v222
	v_mul_f32_e32 v222, 0xbfb8aa3b, v222
	v_add_f32_e32 v224, 1.0, v224
	v_exp_f32_e32 v222, v222
	v_add_f32_e32 v220, 1.0, v220
	v_rcp_f32_e32 v224, v224
	v_mul_f32_e32 v220, v221, v220
	v_cndmask_b32_e64 v220, v220, v221, s[6:7]
	v_lshlrev_b32_e32 v221, 16, v227
	v_mul_f32_e32 v66, v66, v220
	v_add_f32_e32 v220, 1.0, v222
	v_mul_f32_e32 v221, 0xbfb8aa3b, v221
	v_mul_f32_e32 v220, v224, v220
	v_exp_f32_e32 v221, v221
	v_cndmask_b32_e64 v220, v220, v224, s[6:7]
	v_and_b32_e32 v222, 0xffff0000, v227
	v_mul_f32_e32 v67, v67, v220
	v_lshlrev_b32_e32 v220, 16, v223
	v_mul_f32_e32 v222, 0xbfb8aa3b, v222
	v_mul_f32_e32 v220, 0xbfb8aa3b, v220
	v_exp_f32_e32 v222, v222
	v_add_f32_e32 v221, 1.0, v221
	v_exp_f32_e32 v220, v220
	v_rcp_f32_e32 v221, v221
	v_and_b32_e32 v223, 0xffff0000, v223
	v_mul_f32_e32 v223, 0xbfb8aa3b, v223
	v_add_f32_e32 v222, 1.0, v222
	v_exp_f32_e32 v223, v223
	v_add_f32_e32 v220, 1.0, v220
	v_rcp_f32_e32 v222, v222
	v_mul_f32_e32 v220, v221, v220
	v_cndmask_b32_e64 v220, v220, v221, s[6:7]
	v_mul_f32_e32 v68, v68, v220
	v_add_f32_e32 v220, 1.0, v223
	v_mul_f32_e32 v220, v222, v220
	v_cndmask_b32_e64 v220, v220, v222, s[6:7]
	s_and_b64 vcc, exec, s[8:9]
	v_mul_f32_e32 v69, v69, v220
	s_cbranch_vccnz .LBB0_492
	v_cvt_pk_bf16_f32 v220, v70, v71
	v_cvt_pk_bf16_f32 v221, v72, v73
	v_cvt_pk_bf16_f32 v222, v66, v67
	v_cvt_pk_bf16_f32 v223, v68, v69
	global_store_dwordx4 v[228:229], v[220:223], off offset:256
.LBB0_492:
	s_waitcnt vmcnt(0)
	s_and_b64 vcc, exec, s[6:7]
	s_cbranch_vccz .Lef_w2
	v_mov_b64_e32 v[154:155], v[158:159]
	v_mov_b64_e32 v[156:157], v[160:161]
	v_mov_b64_e32 v[146:147], v[150:151]
	v_mov_b64_e32 v[148:149], v[152:153]
	v_mov_b64_e32 v[138:139], v[142:143]
	v_mov_b64_e32 v[140:141], v[144:145]
	v_mov_b64_e32 v[130:131], v[134:135]
	v_mov_b64_e32 v[132:133], v[136:137]
; __device__ __forceinline__ unsigned cvt_pk_bf16(float lo, float hi) { unsigned r; asm volatile("v_cvt_pk_bf16_f32 %0, %1, %2" : "=v"(r) : "v"(lo), "v"(hi)); return r; }
; __device__ __forceinline__ float bf_lo(unsigned w) { return __uint_as_float(w << 16); }
; __device__ __forceinline__ float bf_hi(unsigned w) { return __uint_as_float(w & 0xffff0000u); }
; __device__ __forceinline__ float gfac(float g1, float g2, bool fin) { const float d1 = __builtin_amdgcn_rcpf(1.0f + __expf(-g1)); return fin ? d1 : d1 * (1.0f + __expf(-g2)); }
;     __device__ __forceinline__ void operator()(f32x4 (&acc)[2][2][4][2], const Unit& u, int wr, int wc, int fr, int fq) const {
;     ...
;                 for (int mi = 0; mi < 2; ++mi) { const int row = row0 + ai * HALF + (2 * mp + mi) * 16; const unsigned goff = ((unsigned)row * (unsigned)ldg + (unsigned)col0) * 2u;
; #pragma unroll
;                     for (int bj = 0; bj < 2; ++bj) { x1[mi][bj] = *(const u32x4*)(g1 + goff + bj * HALF * 2); x2[mi][bj] = x1[mi][bj]; if (!fin) x2[mi][bj] = *(const u32x4*)(g2 + goff + bj * HALF * 2); } }
; #pragma unroll
;                 for (int mi = 0; mi < 2; ++mi) { const int m = 2 * mp + mi; const int row = row0 + ai * HALF + m * 16; const unsigned moff = ((unsigned)row * 2048u + (unsigned)col0) * 2u;
; #pragma unroll
;                     for (int bj = 0; bj < 2; ++bj) { const u32x4 p = x1[mi][bj], q = x2[mi][bj];
;                         f32x4 a0 = acc[ai][bj][m][0], a1 = acc[ai][bj][m][1];
;                         a0[0] *= gfac(bf_lo(p.x), bf_lo(q.x), fin); a0[1] *= gfac(bf_hi(p.x), bf_hi(q.x), fin); a0[2] *= gfac(bf_lo(p.y), bf_lo(q.y), fin); a0[3] *= gfac(bf_hi(p.y), bf_hi(q.y), fin);
;                         a1[0] *= gfac(bf_lo(p.z), bf_lo(q.z), fin); a1[1] *= gfac(bf_hi(p.z), bf_hi(q.z), fin); a1[2] *= gfac(bf_lo(p.w), bf_lo(q.w), fin); a1[3] *= gfac(bf_hi(p.w), bf_hi(q.w), fin);
;                         acc[ai][bj][m][0] = a0; acc[ai][bj][m][1] = a1;
;                         if (fin) { u32x4 w; w.x = cvt_pk_bf16(a0[0], a0[1]); w.y = cvt_pk_bf16(a0[2], a0[3]); w.z = cvt_pk_bf16(a1[0], a1[1]); w.w = cvt_pk_bf16(a1[2], a1[3]);
;                             *(u32x4*)((char*)MG + moff + bj * HALF * 2) = w; } } }
.Lef_w2:
	s_nop 1
	v_lshl_add_u32 v164, v194, 1, v218
	global_load_dwordx4 v[248:251], v164, s[34:35]
	v_mov_b32_e32 v165, v32
	v_lshl_add_u64 v[166:167], s[36:37], 0, v[164:165]
	v_lshl_add_u64 v[164:165], s[34:35], 0, v[164:165]
	global_load_dwordx4 v[240:243], v[164:165], off offset:256
	v_lshl_add_u32 v164, v194, 1, v219
	global_load_dwordx4 v[232:235], v164, s[34:35]
	v_mov_b32_e32 v165, v32
	v_lshl_add_u64 v[194:195], s[36:37], 0, v[164:165]
	v_lshl_add_u64 v[164:165], s[34:35], 0, v[164:165]
	global_load_dwordx4 v[224:227], v[164:165], off offset:256
	s_and_b64 vcc, exec, s[6:7]
	s_cbranch_vccnz .Lef_i3
	global_load_dwordx4 v[244:247], v[166:167], off
	global_load_dwordx4 v[236:239], v[166:167], off offset:256
	global_load_dwordx4 v[228:231], v[194:195], off
	global_load_dwordx4 v[220:223], v[194:195], off offset:256
.Lef_i3:
.LBB0_500:
	v_lshlrev_b32_e32 v164, 16, v158
	v_mul_f32_e32 v164, 0xbfb8aa3b, v164
	v_exp_f32_e32 v166, v164
	v_lshlrev_b32_e32 v167, 16, v154
	v_and_b32_e32 v158, 0xffff0000, v158
	v_mul_f32_e32 v167, 0xbfb8aa3b, v167
	v_mul_f32_e32 v158, 0xbfb8aa3b, v158
	v_add_f32_e32 v166, 1.0, v166
	v_exp_f32_e32 v167, v167
	v_exp_f32_e32 v158, v158
	v_rcp_f32_e32 v166, v166
	v_and_b32_e32 v154, 0xffff0000, v154
	v_mul_f32_e32 v154, 0xbfb8aa3b, v154
	v_add_f32_e32 v167, 1.0, v167
	v_add_f32_e32 v158, 1.0, v158
	v_exp_f32_e32 v154, v154
	v_mul_f32_e32 v167, v166, v167
	v_rcp_f32_e32 v158, v158
	v_cndmask_b32_e64 v166, v167, v166, s[6:7]
	v_mul_f32_e32 v62, v62, v166
	v_lshlrev_b32_e32 v166, 16, v159
	v_add_f32_e32 v154, 1.0, v154
	v_mul_f32_e32 v166, 0xbfb8aa3b, v166
	v_mul_f32_e32 v154, v158, v154
	v_exp_f32_e32 v166, v166
	v_cndmask_b32_e64 v154, v154, v158, s[6:7]
	v_mul_f32_e32 v63, v63, v154
	v_lshlrev_b32_e32 v154, 16, v155
	v_and_b32_e32 v159, 0xffff0000, v159
	v_mul_f32_e32 v154, 0xbfb8aa3b, v154
	v_mul_f32_e32 v159, 0xbfb8aa3b, v159
	v_add_f32_e32 v158, 1.0, v166
	v_exp_f32_e32 v154, v154
	v_exp_f32_e32 v159, v159
	v_rcp_f32_e32 v158, v158
	v_and_b32_e32 v155, 0xffff0000, v155
	v_mul_f32_e32 v155, 0xbfb8aa3b, v155
	v_exp_f32_e32 v155, v155
	v_add_f32_e32 v154, 1.0, v154
	v_add_f32_e32 v159, 1.0, v159
	v_mul_f32_e32 v154, v158, v154
	v_rcp_f32_e32 v159, v159
	v_cndmask_b32_e64 v154, v154, v158, s[6:7]
	v_mul_f32_e32 v64, v64, v154
	v_add_f32_e32 v154, 1.0, v155
	v_lshlrev_b32_e32 v155, 16, v160
	v_mul_f32_e32 v155, 0xbfb8aa3b, v155
	v_mul_f32_e32 v154, v159, v154
	v_exp_f32_e32 v155, v155
	v_cndmask_b32_e64 v154, v154, v159, s[6:7]
	v_and_b32_e32 v158, 0xffff0000, v160
	v_mul_f32_e32 v65, v65, v154
	v_lshlrev_b32_e32 v154, 16, v156
	v_mul_f32_e32 v158, 0xbfb8aa3b, v158
	v_mul_f32_e32 v154, 0xbfb8aa3b, v154
	v_exp_f32_e32 v158, v158
	v_add_f32_e32 v155, 1.0, v155
	v_exp_f32_e32 v154, v154
	v_rcp_f32_e32 v155, v155
	v_and_b32_e32 v156, 0xffff0000, v156
	v_mul_f32_e32 v156, 0xbfb8aa3b, v156
	v_add_f32_e32 v158, 1.0, v158
	v_exp_f32_e32 v156, v156
	v_add_f32_e32 v154, 1.0, v154
	v_rcp_f32_e32 v158, v158
	v_mul_f32_e32 v154, v155, v154
	v_cndmask_b32_e64 v154, v154, v155, s[6:7]
	v_lshlrev_b32_e32 v155, 16, v161
	v_mul_f32_e32 v58, v58, v154
	v_add_f32_e32 v154, 1.0, v156
	v_mul_f32_e32 v155, 0xbfb8aa3b, v155
	v_mul_f32_e32 v154, v158, v154
	v_exp_f32_e32 v155, v155
	v_cndmask_b32_e64 v154, v154, v158, s[6:7]
	v_and_b32_e32 v156, 0xffff0000, v161
	v_mul_f32_e32 v59, v59, v154
	v_lshlrev_b32_e32 v154, 16, v157
	v_mul_f32_e32 v156, 0xbfb8aa3b, v156
	v_mul_f32_e32 v154, 0xbfb8aa3b, v154
	v_exp_f32_e32 v156, v156
	v_add_f32_e32 v155, 1.0, v155
	v_exp_f32_e32 v154, v154
	v_rcp_f32_e32 v155, v155
	v_and_b32_e32 v157, 0xffff0000, v157
	v_mul_f32_e32 v157, 0xbfb8aa3b, v157
	v_add_f32_e32 v156, 1.0, v156
	v_exp_f32_e32 v157, v157
	v_add_f32_e32 v154, 1.0, v154
	v_rcp_f32_e32 v156, v156
	v_mul_f32_e32 v154, v155, v154
	v_cndmask_b32_e64 v154, v154, v155, s[6:7]
	v_mul_f32_e32 v60, v60, v154
	v_add_f32_e32 v154, 1.0, v157
	v_mul_f32_e32 v154, v156, v154
	v_add_u32_e32 v164, 0x80000, v192
	v_mov_b32_e32 v165, v32
	v_cndmask_b32_e64 v154, v154, v156, s[6:7]
	v_mul_f32_e32 v61, v61, v154
	s_and_b64 vcc, exec, s[8:9]
	v_lshl_add_u64 v[154:155], s[16:17], 0, v[164:165]
	s_cbranch_vccnz .LBB0_502
	v_cvt_pk_bf16_f32 v156, v62, v63
	v_cvt_pk_bf16_f32 v157, v64, v65
	v_cvt_pk_bf16_f32 v158, v58, v59
	v_cvt_pk_bf16_f32 v159, v60, v61
	global_store_dwordx4 v[154:155], v[156:159], off

; __device__ __forceinline__ unsigned cvt_pk_bf16(float lo, float hi) { unsigned r; asm volatile("v_cvt_pk_bf16_f32 %0, %1, %2" : "=v"(r) : "v"(lo), "v"(hi)); return r; }
; __device__ __forceinline__ float bf_lo(unsigned w) { return __uint_as_float(w << 16); }
; __device__ __forceinline__ float bf_hi(unsigned w) { return __uint_as_float(w & 0xffff0000u); }
; __device__ __forceinline__ float gfac(float g1, float g2, bool fin) { const float d1 = __builtin_amdgcn_rcpf(1.0f + __expf(-g1)); return fin ? d1 : d1 * (1.0f + __expf(-g2)); }
;     __device__ __forceinline__ void operator()(f32x4 (&acc)[2][2][4][2], const Unit& u, int wr, int wc, int fr, int fq) const {
;     ...
; #pragma unroll
;                 for (int mi = 0; mi < 2; ++mi) { const int m = 2 * mp + mi; const int row = row0 + ai * HALF + m * 16; const unsigned moff = ((unsigned)row * 2048u + (unsigned)col0) * 2u;
; #pragma unroll
;                     for (int bj = 0; bj < 2; ++bj) { const u32x4 p = x1[mi][bj], q = x2[mi][bj];
;                         f32x4 a0 = acc[ai][bj][m][0], a1 = acc[ai][bj][m][1];
;                         a0[0] *= gfac(bf_lo(p.x), bf_lo(q.x), fin); a0[1] *= gfac(bf_hi(p.x), bf_hi(q.x), fin); a0[2] *= gfac(bf_lo(p.y), bf_lo(q.y), fin); a0[3] *= gfac(bf_hi(p.y), bf_hi(q.y), fin);
;                         a1[0] *= gfac(bf_lo(p.z), bf_lo(q.z), fin); a1[1] *= gfac(bf_hi(p.z), bf_hi(q.z), fin); a1[2] *= gfac(bf_lo(p.w), bf_lo(q.w), fin); a1[3] *= gfac(bf_hi(p.w), bf_hi(q.w), fin);
;                         acc[ai][bj][m][0] = a0; acc[ai][bj][m][1] = a1;
;                         if (fin) { u32x4 w; w.x = cvt_pk_bf16(a0[0], a0[1]); w.y = cvt_pk_bf16(a0[2], a0[3]); w.z = cvt_pk_bf16(a1[0], a1[1]); w.w = cvt_pk_bf16(a1[2], a1[3]);
;                             *(u32x4*)((char*)MG + moff + bj * HALF * 2) = w; } } }
.Lef_w3:
.LBB0_516:
	v_lshlrev_b32_e32 v164, 16, v248
	v_mul_f32_e32 v164, 0xbfb8aa3b, v164
	v_exp_f32_e32 v166, v164
	v_lshlrev_b32_e32 v167, 16, v244
	v_and_b32_e32 v248, 0xffff0000, v248
	v_mul_f32_e32 v167, 0xbfb8aa3b, v167
	v_mul_f32_e32 v248, 0xbfb8aa3b, v248
	v_add_f32_e32 v166, 1.0, v166
	v_exp_f32_e32 v167, v167
	v_exp_f32_e32 v248, v248
	v_rcp_f32_e32 v166, v166
	v_and_b32_e32 v244, 0xffff0000, v244
	v_mul_f32_e32 v244, 0xbfb8aa3b, v244
	v_add_f32_e32 v167, 1.0, v167
	v_add_f32_e32 v248, 1.0, v248
	v_exp_f32_e32 v244, v244
	v_mul_f32_e32 v167, v166, v167
	v_rcp_f32_e32 v248, v248
	v_cndmask_b32_e64 v166, v167, v166, s[6:7]
	v_mul_f32_e32 v46, v46, v166
	v_lshlrev_b32_e32 v166, 16, v249
	v_add_f32_e32 v244, 1.0, v244
	v_mul_f32_e32 v166, 0xbfb8aa3b, v166
	v_mul_f32_e32 v244, v248, v244
	v_exp_f32_e32 v166, v166
	v_cndmask_b32_e64 v244, v244, v248, s[6:7]
	v_mul_f32_e32 v47, v47, v244
	v_lshlrev_b32_e32 v244, 16, v245
	v_and_b32_e32 v249, 0xffff0000, v249
	v_mul_f32_e32 v244, 0xbfb8aa3b, v244
	v_mul_f32_e32 v249, 0xbfb8aa3b, v249
	v_add_f32_e32 v248, 1.0, v166
	v_exp_f32_e32 v244, v244
	v_exp_f32_e32 v249, v249
	v_rcp_f32_e32 v248, v248
	v_and_b32_e32 v245, 0xffff0000, v245
	v_mul_f32_e32 v245, 0xbfb8aa3b, v245
	v_exp_f32_e32 v245, v245
	v_add_f32_e32 v244, 1.0, v244
	v_add_f32_e32 v249, 1.0, v249
	v_mul_f32_e32 v244, v248, v244
	v_rcp_f32_e32 v249, v249
	v_cndmask_b32_e64 v244, v244, v248, s[6:7]
	v_mul_f32_e32 v48, v48, v244
	v_add_f32_e32 v244, 1.0, v245
	v_lshlrev_b32_e32 v245, 16, v250
	v_mul_f32_e32 v245, 0xbfb8aa3b, v245
	v_mul_f32_e32 v244, v249, v244
	v_exp_f32_e32 v245, v245
	v_cndmask_b32_e64 v244, v244, v249, s[6:7]
	v_and_b32_e32 v248, 0xffff0000, v250
	v_mul_f32_e32 v49, v49, v244
	v_lshlrev_b32_e32 v244, 16, v246
	v_mul_f32_e32 v248, 0xbfb8aa3b, v248
	v_mul_f32_e32 v244, 0xbfb8aa3b, v244
	v_exp_f32_e32 v248, v248
	v_add_f32_e32 v245, 1.0, v245
	v_exp_f32_e32 v244, v244
	v_rcp_f32_e32 v245, v245
	v_and_b32_e32 v246, 0xffff0000, v246
	v_mul_f32_e32 v246, 0xbfb8aa3b, v246
	v_add_f32_e32 v248, 1.0, v248
	v_exp_f32_e32 v246, v246
	v_add_f32_e32 v244, 1.0, v244
	v_rcp_f32_e32 v248, v248
	v_mul_f32_e32 v244, v245, v244
	v_cndmask_b32_e64 v244, v244, v245, s[6:7]
	v_lshlrev_b32_e32 v245, 16, v251
	v_mul_f32_e32 v42, v42, v244
	v_add_f32_e32 v244, 1.0, v246
	v_mul_f32_e32 v245, 0xbfb8aa3b, v245
	v_mul_f32_e32 v244, v248, v244
	v_exp_f32_e32 v245, v245
	v_cndmask_b32_e64 v244, v244, v248, s[6:7]
	v_and_b32_e32 v246, 0xffff0000, v251
	v_mul_f32_e32 v43, v43, v244
	v_lshlrev_b32_e32 v244, 16, v247
	v_mul_f32_e32 v246, 0xbfb8aa3b, v246
	v_mul_f32_e32 v244, 0xbfb8aa3b, v244
	v_exp_f32_e32 v246, v246
	v_add_f32_e32 v245, 1.0, v245
	v_exp_f32_e32 v244, v244
	v_rcp_f32_e32 v245, v245
	v_and_b32_e32 v247, 0xffff0000, v247
	v_mul_f32_e32 v247, 0xbfb8aa3b, v247
	v_add_f32_e32 v246, 1.0, v246
	v_exp_f32_e32 v247, v247
	v_add_f32_e32 v244, 1.0, v244
	v_rcp_f32_e32 v246, v246
	v_mul_f32_e32 v244, v245, v244
	v_cndmask_b32_e64 v244, v244, v245, s[6:7]
	v_mul_f32_e32 v44, v44, v244
	v_add_f32_e32 v244, 1.0, v247
	v_mul_f32_e32 v244, v246, v244
	v_add_u32_e32 v164, 0xa0000, v192
	v_mov_b32_e32 v165, v32
	v_cndmask_b32_e64 v244, v244, v246, s[6:7]
	v_mul_f32_e32 v45, v45, v244
	s_and_b64 vcc, exec, s[8:9]
	v_lshl_add_u64 v[244:245], s[16:17], 0, v[164:165]
	s_cbranch_vccnz .LBB0_518
	v_cvt_pk_bf16_f32 v246, v46, v47
	v_cvt_pk_bf16_f32 v247, v48, v49
	v_cvt_pk_bf16_f32 v248, v42, v43
	v_cvt_pk_bf16_f32 v249, v44, v45
	global_store_dwordx4 v[244:245], v[246:249], off
.LBB0_518:
	s_nop 1
	v_lshlrev_b32_e32 v246, 16, v240
	v_mul_f32_e32 v246, 0xbfb8aa3b, v246
	v_exp_f32_e32 v246, v246
	v_lshlrev_b32_e32 v247, 16, v236
	v_and_b32_e32 v240, 0xffff0000, v240
	v_mul_f32_e32 v247, 0xbfb8aa3b, v247
	v_mul_f32_e32 v240, 0xbfb8aa3b, v240
	v_exp_f32_e32 v247, v247
	v_add_f32_e32 v246, 1.0, v246
	v_exp_f32_e32 v240, v240
	v_rcp_f32_e32 v246, v246
	v_and_b32_e32 v236, 0xffff0000, v236
	v_mul_f32_e32 v236, 0xbfb8aa3b, v236
	v_add_f32_e32 v247, 1.0, v247
	v_add_f32_e32 v240, 1.0, v240
	v_exp_f32_e32 v236, v236
	v_mul_f32_e32 v247, v246, v247
	v_rcp_f32_e32 v240, v240
	v_cndmask_b32_e64 v246, v247, v246, s[6:7]
	v_mul_f32_e32 v12, v12, v246
	v_lshlrev_b32_e32 v246, 16, v241
	v_add_f32_e32 v236, 1.0, v236
	v_mul_f32_e32 v246, 0xbfb8aa3b, v246
	v_mul_f32_e32 v236, v240, v236
	v_exp_f32_e32 v246, v246
	v_cndmask_b32_e64 v236, v236, v240, s[6:7]
	v_mul_f32_e32 v13, v13, v236
	v_lshlrev_b32_e32 v236, 16, v237
	v_and_b32_e32 v241, 0xffff0000, v241
	v_mul_f32_e32 v236, 0xbfb8aa3b, v236
	v_mul_f32_e32 v241, 0xbfb8aa3b, v241
	v_add_f32_e32 v240, 1.0, v246
	v_exp_f32_e32 v236, v236
	v_exp_f32_e32 v241, v241
	v_rcp_f32_e32 v240, v240
	v_and_b32_e32 v237, 0xffff0000, v237
	v_mul_f32_e32 v237, 0xbfb8aa3b, v237
	v_exp_f32_e32 v237, v237
	v_add_f32_e32 v236, 1.0, v236
	v_add_f32_e32 v241, 1.0, v241
	v_mul_f32_e32 v236, v240, v236
	v_rcp_f32_e32 v241, v241
	v_cndmask_b32_e64 v236, v236, v240, s[6:7]
	v_mul_f32_e32 v14, v14, v236
	v_add_f32_e32 v236, 1.0, v237
	v_lshlrev_b32_e32 v237, 16, v242
	v_mul_f32_e32 v237, 0xbfb8aa3b, v237
	v_mul_f32_e32 v236, v241, v236
	v_exp_f32_e32 v237, v237
	v_cndmask_b32_e64 v236, v236, v241, s[6:7]
	v_and_b32_e32 v240, 0xffff0000, v242
	v_mul_f32_e32 v15, v15, v236
	v_lshlrev_b32_e32 v236, 16, v238
	v_mul_f32_e32 v240, 0xbfb8aa3b, v240
	v_mul_f32_e32 v236, 0xbfb8aa3b, v236
	v_exp_f32_e32 v240, v240
	v_add_f32_e32 v237, 1.0, v237
	v_exp_f32_e32 v236, v236
	v_rcp_f32_e32 v237, v237
	v_and_b32_e32 v238, 0xffff0000, v238
	v_mul_f32_e32 v238, 0xbfb8aa3b, v238
	v_add_f32_e32 v240, 1.0, v240
	v_exp_f32_e32 v238, v238
	v_add_f32_e32 v236, 1.0, v236
	v_rcp_f32_e32 v240, v240
	v_mul_f32_e32 v236, v237, v236
	v_cndmask_b32_e64 v236, v236, v237, s[6:7]
	v_lshlrev_b32_e32 v237, 16, v243
	v_mul_f32_e32 v8, v8, v236
	v_add_f32_e32 v236, 1.0, v238
	v_mul_f32_e32 v237, 0xbfb8aa3b, v237
	v_mul_f32_e32 v236, v240, v236
	v_exp_f32_e32 v237, v237
	v_cndmask_b32_e64 v236, v236, v240, s[6:7]
	v_and_b32_e32 v238, 0xffff0000, v243
	v_mul_f32_e32 v9, v9, v236
	v_lshlrev_b32_e32 v236, 16, v239
	v_mul_f32_e32 v238, 0xbfb8aa3b, v238
	v_mul_f32_e32 v236, 0xbfb8aa3b, v236
	v_exp_f32_e32 v238, v238
	v_add_f32_e32 v237, 1.0, v237
	v_exp_f32_e32 v236, v236
	v_rcp_f32_e32 v237, v237
	v_and_b32_e32 v239, 0xffff0000, v239
	v_mul_f32_e32 v239, 0xbfb8aa3b, v239
	v_add_f32_e32 v238, 1.0, v238
	v_exp_f32_e32 v239, v239
	v_add_f32_e32 v236, 1.0, v236
	v_rcp_f32_e32 v238, v238
	v_mul_f32_e32 v236, v237, v236
	v_cndmask_b32_e64 v236, v236, v237, s[6:7]
	v_mul_f32_e32 v10, v10, v236
	v_add_f32_e32 v236, 1.0, v239
	v_mul_f32_e32 v236, v238, v236
	v_cndmask_b32_e64 v236, v236, v238, s[6:7]
	s_and_b64 vcc, exec, s[8:9]
	v_mul_f32_e32 v11, v11, v236
	s_cbranch_vccnz .LBB0_520
	v_cvt_pk_bf16_f32 v236, v12, v13
	v_cvt_pk_bf16_f32 v237, v14, v15
	v_cvt_pk_bf16_f32 v238, v8, v9
	v_cvt_pk_bf16_f32 v239, v10, v11
	global_store_dwordx4 v[244:245], v[236:239], off offset:256
; __device__ __forceinline__ unsigned cvt_pk_bf16(float lo, float hi) { unsigned r; asm volatile("v_cvt_pk_bf16_f32 %0, %1, %2" : "=v"(r) : "v"(lo), "v"(hi)); return r; }
; __device__ __forceinline__ float bf_lo(unsigned w) { return __uint_as_float(w << 16); }
; __device__ __forceinline__ float bf_hi(unsigned w) { return __uint_as_float(w & 0xffff0000u); }
; __device__ __forceinline__ float gfac(float g1, float g2, bool fin) { const float d1 = __builtin_amdgcn_rcpf(1.0f + __expf(-g1)); return fin ? d1 : d1 * (1.0f + __expf(-g2)); }
;     __device__ __forceinline__ void operator()(f32x4 (&acc)[2][2][4][2], const Unit& u, int wr, int wc, int fr, int fq) const {
;     ...
;                     for (int bj = 0; bj < 2; ++bj) { const u32x4 p = x1[mi][bj], q = x2[mi][bj];
;                         f32x4 a0 = acc[ai][bj][m][0], a1 = acc[ai][bj][m][1];
;                         a0[0] *= gfac(bf_lo(p.x), bf_lo(q.x), fin); a0[1] *= gfac(bf_hi(p.x), bf_hi(q.x), fin); a0[2] *= gfac(bf_lo(p.y), bf_lo(q.y), fin); a0[3] *= gfac(bf_hi(p.y), bf_hi(q.y), fin);
;                         a1[0] *= gfac(bf_lo(p.z), bf_lo(q.z), fin); a1[1] *= gfac(bf_hi(p.z), bf_hi(q.z), fin); a1[2] *= gfac(bf_lo(p.w), bf_lo(q.w), fin); a1[3] *= gfac(bf_hi(p.w), bf_hi(q.w), fin);
;                         acc[ai][bj][m][0] = a0; acc[ai][bj][m][1] = a1;
;                         if (fin) { u32x4 w; w.x = cvt_pk_bf16(a0[0], a0[1]); w.y = cvt_pk_bf16(a0[2], a0[3]); w.z = cvt_pk_bf16(a1[0], a1[1]); w.w = cvt_pk_bf16(a1[2], a1[3]);
;                             *(u32x4*)((char*)MG + moff + bj * HALF * 2) = w; } } }
.LBB0_520:
	s_nop 1
	v_lshlrev_b32_e32 v236, 16, v232
	v_mul_f32_e32 v236, 0xbfb8aa3b, v236
	v_exp_f32_e32 v238, v236
	v_lshlrev_b32_e32 v239, 16, v228
	v_and_b32_e32 v232, 0xffff0000, v232
	v_mul_f32_e32 v239, 0xbfb8aa3b, v239
	v_mul_f32_e32 v232, 0xbfb8aa3b, v232
	v_add_f32_e32 v238, 1.0, v238
	v_exp_f32_e32 v239, v239
	v_exp_f32_e32 v232, v232
	v_rcp_f32_e32 v238, v238
	v_and_b32_e32 v228, 0xffff0000, v228
	v_mul_f32_e32 v228, 0xbfb8aa3b, v228
	v_add_f32_e32 v239, 1.0, v239
	v_add_f32_e32 v232, 1.0, v232
	v_exp_f32_e32 v228, v228
	v_mul_f32_e32 v239, v238, v239
	v_rcp_f32_e32 v232, v232
	v_cndmask_b32_e64 v238, v239, v238, s[6:7]
	v_mul_f32_e32 v38, v38, v238
	v_lshlrev_b32_e32 v238, 16, v233
	v_add_f32_e32 v228, 1.0, v228
	v_mul_f32_e32 v238, 0xbfb8aa3b, v238
	v_mul_f32_e32 v228, v232, v228
	v_exp_f32_e32 v238, v238
	v_cndmask_b32_e64 v228, v228, v232, s[6:7]
	v_mul_f32_e32 v39, v39, v228
	v_lshlrev_b32_e32 v228, 16, v229
	v_and_b32_e32 v233, 0xffff0000, v233
	v_mul_f32_e32 v228, 0xbfb8aa3b, v228
	v_mul_f32_e32 v233, 0xbfb8aa3b, v233
	v_add_f32_e32 v232, 1.0, v238
	v_exp_f32_e32 v228, v228
	v_exp_f32_e32 v233, v233
	v_rcp_f32_e32 v232, v232
	v_and_b32_e32 v229, 0xffff0000, v229
	v_mul_f32_e32 v229, 0xbfb8aa3b, v229
	v_exp_f32_e32 v229, v229
	v_add_f32_e32 v228, 1.0, v228
	v_add_f32_e32 v233, 1.0, v233
	v_mul_f32_e32 v228, v232, v228
	v_rcp_f32_e32 v233, v233
	v_cndmask_b32_e64 v228, v228, v232, s[6:7]
	v_mul_f32_e32 v40, v40, v228
	v_add_f32_e32 v228, 1.0, v229
	v_lshlrev_b32_e32 v229, 16, v234
	v_mul_f32_e32 v229, 0xbfb8aa3b, v229
	v_mul_f32_e32 v228, v233, v228
	v_exp_f32_e32 v229, v229
	v_cndmask_b32_e64 v228, v228, v233, s[6:7]
	v_and_b32_e32 v232, 0xffff0000, v234
	v_mul_f32_e32 v41, v41, v228
	v_lshlrev_b32_e32 v228, 16, v230
	v_mul_f32_e32 v232, 0xbfb8aa3b, v232
	v_mul_f32_e32 v228, 0xbfb8aa3b, v228
	v_exp_f32_e32 v232, v232
	v_add_f32_e32 v229, 1.0, v229
	v_exp_f32_e32 v228, v228
	v_rcp_f32_e32 v229, v229
	v_and_b32_e32 v230, 0xffff0000, v230
	v_mul_f32_e32 v230, 0xbfb8aa3b, v230
	v_add_f32_e32 v232, 1.0, v232
	v_exp_f32_e32 v230, v230
	v_add_f32_e32 v228, 1.0, v228
	v_rcp_f32_e32 v232, v232
	v_mul_f32_e32 v228, v229, v228
	v_cndmask_b32_e64 v228, v228, v229, s[6:7]
	v_lshlrev_b32_e32 v229, 16, v235
	v_mul_f32_e32 v34, v34, v228
	v_add_f32_e32 v228, 1.0, v230
	v_mul_f32_e32 v229, 0xbfb8aa3b, v229
	v_mul_f32_e32 v228, v232, v228
	v_exp_f32_e32 v229, v229
	v_cndmask_b32_e64 v228, v228, v232, s[6:7]
	v_and_b32_e32 v230, 0xffff0000, v235
	v_mul_f32_e32 v35, v35, v228
	v_lshlrev_b32_e32 v228, 16, v231
	v_mul_f32_e32 v230, 0xbfb8aa3b, v230
	v_mul_f32_e32 v228, 0xbfb8aa3b, v228
	v_exp_f32_e32 v230, v230
	v_add_f32_e32 v229, 1.0, v229
	v_exp_f32_e32 v228, v228
	v_rcp_f32_e32 v229, v229
	v_and_b32_e32 v231, 0xffff0000, v231
	v_mul_f32_e32 v231, 0xbfb8aa3b, v231
	v_add_f32_e32 v230, 1.0, v230
	v_exp_f32_e32 v231, v231
	v_add_f32_e32 v228, 1.0, v228
	v_rcp_f32_e32 v230, v230
	v_mul_f32_e32 v228, v229, v228
	v_cndmask_b32_e64 v228, v228, v229, s[6:7]
	v_mul_f32_e32 v36, v36, v228
	v_add_f32_e32 v228, 1.0, v231
	v_mul_f32_e32 v228, v230, v228
	v_add_u32_e32 v236, 0xb0000, v192
	v_mov_b32_e32 v237, v32
	v_cndmask_b32_e64 v228, v228, v230, s[6:7]
	v_mul_f32_e32 v37, v37, v228
	s_and_b64 vcc, exec, s[8:9]
	v_lshl_add_u64 v[228:229], s[16:17], 0, v[236:237]
	s_cbranch_vccnz .LBB0_522
	v_cvt_pk_bf16_f32 v230, v38, v39
	v_cvt_pk_bf16_f32 v231, v40, v41
	v_cvt_pk_bf16_f32 v232, v34, v35
	v_cvt_pk_bf16_f32 v233, v36, v37
	global_store_dwordx4 v[228:229], v[230:233], off
.LBB0_522:
	s_nop 1
	v_lshlrev_b32_e32 v230, 16, v224
	v_mul_f32_e32 v230, 0xbfb8aa3b, v230
	v_exp_f32_e32 v230, v230
	s_waitcnt vmcnt(0)
	v_lshlrev_b32_e32 v231, 16, v220
	v_and_b32_e32 v224, 0xffff0000, v224
	v_mul_f32_e32 v231, 0xbfb8aa3b, v231
	v_mul_f32_e32 v224, 0xbfb8aa3b, v224
	v_exp_f32_e32 v231, v231
	v_add_f32_e32 v230, 1.0, v230
	v_exp_f32_e32 v224, v224
	v_rcp_f32_e32 v230, v230
	v_and_b32_e32 v220, 0xffff0000, v220
	v_mul_f32_e32 v220, 0xbfb8aa3b, v220
	v_add_f32_e32 v231, 1.0, v231
	v_add_f32_e32 v224, 1.0, v224
	v_exp_f32_e32 v220, v220
	v_mul_f32_e32 v231, v230, v231
	v_rcp_f32_e32 v224, v224
	v_cndmask_b32_e64 v230, v231, v230, s[6:7]
	v_mul_f32_e32 v4, v4, v230
	v_lshlrev_b32_e32 v230, 16, v225
	v_add_f32_e32 v220, 1.0, v220
	v_mul_f32_e32 v230, 0xbfb8aa3b, v230
	v_mul_f32_e32 v220, v224, v220
	v_exp_f32_e32 v230, v230
	v_cndmask_b32_e64 v220, v220, v224, s[6:7]
	v_mul_f32_e32 v5, v5, v220
	v_lshlrev_b32_e32 v220, 16, v221
	v_and_b32_e32 v225, 0xffff0000, v225
	v_mul_f32_e32 v220, 0xbfb8aa3b, v220
	v_mul_f32_e32 v225, 0xbfb8aa3b, v225
	v_add_f32_e32 v224, 1.0, v230
	v_exp_f32_e32 v220, v220
	v_exp_f32_e32 v225, v225
	v_rcp_f32_e32 v224, v224
	v_and_b32_e32 v221, 0xffff0000, v221
	v_mul_f32_e32 v221, 0xbfb8aa3b, v221
	v_exp_f32_e32 v221, v221
	v_add_f32_e32 v220, 1.0, v220
	v_add_f32_e32 v225, 1.0, v225
	v_mul_f32_e32 v220, v224, v220
	v_rcp_f32_e32 v225, v225
	v_cndmask_b32_e64 v220, v220, v224, s[6:7]
	v_mul_f32_e32 v6, v6, v220
	v_add_f32_e32 v220, 1.0, v221
	v_lshlrev_b32_e32 v221, 16, v226
	v_mul_f32_e32 v221, 0xbfb8aa3b, v221
	v_mul_f32_e32 v220, v225, v220
	v_exp_f32_e32 v221, v221
	v_cndmask_b32_e64 v220, v220, v225, s[6:7]
	v_and_b32_e32 v224, 0xffff0000, v226
	v_mul_f32_e32 v7, v7, v220
	v_lshlrev_b32_e32 v220, 16, v222
	v_mul_f32_e32 v224, 0xbfb8aa3b, v224
	v_mul_f32_e32 v220, 0xbfb8aa3b, v220
	v_exp_f32_e32 v224, v224
	v_add_f32_e32 v221, 1.0, v221
	v_exp_f32_e32 v220, v220
	v_rcp_f32_e32 v221, v221
	v_and_b32_e32 v222, 0xffff0000, v222
	v_mul_f32_e32 v222, 0xbfb8aa3b, v222
	v_add_f32_e32 v224, 1.0, v224
	v_exp_f32_e32 v222, v222
	v_add_f32_e32 v220, 1.0, v220
	v_rcp_f32_e32 v224, v224
	v_mul_f32_e32 v220, v221, v220
	v_cndmask_b32_e64 v220, v220, v221, s[6:7]
	v_lshlrev_b32_e32 v221, 16, v227
	v_mul_f32_e32 v0, v0, v220
	v_add_f32_e32 v220, 1.0, v222
	v_mul_f32_e32 v221, 0xbfb8aa3b, v221
	v_mul_f32_e32 v220, v224, v220
	v_exp_f32_e32 v221, v221
	v_cndmask_b32_e64 v220, v220, v224, s[6:7]
	v_and_b32_e32 v222, 0xffff0000, v227
	v_mul_f32_e32 v1, v1, v220
	v_lshlrev_b32_e32 v220, 16, v223
	v_mul_f32_e32 v222, 0xbfb8aa3b, v222
	v_mul_f32_e32 v220, 0xbfb8aa3b, v220
	v_exp_f32_e32 v222, v222
	v_add_f32_e32 v221, 1.0, v221
	v_exp_f32_e32 v220, v220
	v_rcp_f32_e32 v221, v221
	v_and_b32_e32 v223, 0xffff0000, v223
	v_mul_f32_e32 v223, 0xbfb8aa3b, v223
	v_add_f32_e32 v222, 1.0, v222
	v_exp_f32_e32 v223, v223
	v_add_f32_e32 v220, 1.0, v220
	v_rcp_f32_e32 v222, v222
	v_mul_f32_e32 v220, v221, v220
	v_cndmask_b32_e64 v220, v220, v221, s[6:7]
	v_mul_f32_e32 v2, v2, v220
	v_add_f32_e32 v220, 1.0, v223
	v_mul_f32_e32 v220, v222, v220
	v_cndmask_b32_e64 v220, v220, v222, s[6:7]
	s_and_b64 vcc, exec, s[8:9]
	v_mul_f32_e32 v3, v3, v220
	s_cbranch_vccnz .LBB0_524
	v_cvt_pk_bf16_f32 v220, v4, v5
	v_cvt_pk_bf16_f32 v221, v6, v7
	v_cvt_pk_bf16_f32 v222, v0, v1
	v_cvt_pk_bf16_f32 v223, v2, v3
	global_store_dwordx4 v[228:229], v[220:223], off offset:256
